# D-type phases: whole-unit X tile loaded during the preceding grid barrier wait straight into the accumulator registers; prologue only scales
# baseline (speedup 1.0000x reference)
;     __device__ __forceinline__ void init(f32x4 (&acc)[2][2][4][2], const pg8::Unit& u, int wr, int wc, int fr, int fq) const {
;         const int row0 = u.pm * 256 + wr * 64 + fr, col0 = u.pn * 256 + wc * 32 + 8 * fq; const float inv = 1.0f / scale;
; #pragma unroll
;         for (int ai = 0; ai < 2; ++ai)
; #pragma unroll
;             for (int m = 0; m < 4; ++m)
; #pragma unroll
;                 for (int bj = 0; bj < 2; ++bj) { const float* xp = X + (size_t)(row0 + ai * 128 + m * 16) * D + col0 + bj * 128; acc[ai][bj][m][0] = *(const f32x4*)xp * inv; acc[ai][bj][m][1] = *(const f32x4*)(xp + 4) * inv; }
.LBB0_10:
	s_or_b64 exec, exec, s[0:1]
	s_and_b32 s100, s57, 7
	s_movk_i32 s101, 0xa2
	s_bitcmp1_b32 s101, s100
	s_cbranch_scc0 .Lxpre_skipB
	s_cmp_eq_u32 s70, 0
	s_cbranch_scc0 .Lxpre_skipB
	v_readlane_b32 s100, v254, 4
	v_readlane_b32 s101, v254, 11
	s_lshl_b32 s100, s100, 20
	s_lshl_b32 s101, s101, 10
	s_add_i32 s100, s100, s101
	s_add_i32 s100, s100, 0x2b00000
	s_add_u32 s100, s6, s100
	s_addc_u32 s101, s7, 0
	v_mbcnt_lo_u32_b32 v240, -1, 0
	v_mbcnt_hi_u32_b32 v240, -1, v240
	v_and_b32_e32 v241, 15, v240
	v_bfe_u32 v240, v240, 4, 2
	v_lshlrev_b32_e32 v241, 12, v241
	v_lshl_or_b32 v241, v240, 5, v241
	s_lshr_b32 vcc_lo, s70, 8
	s_lshl_b32 vcc_lo, vcc_lo, 18
	s_bfe_u32 vcc_hi, s70, 0x20006
	s_lshl_b32 vcc_hi, vcc_hi, 7
	s_or_b32 vcc_lo, vcc_lo, vcc_hi
	v_or_b32_e32 v234, vcc_lo, v241
	v_add_u32_e32 v235, 0x10000, v234
	v_add_u32_e32 v236, 0x20000, v234
	v_add_u32_e32 v237, 0x30000, v234
	v_add_u32_e32 v238, 0x80000, v234
	v_add_u32_e32 v239, 0x90000, v234
	v_add_u32_e32 v240, 0xa0000, v234
	v_add_u32_e32 v241, 0xb0000, v234
	global_load_dwordx4 v[230:233], v234, s[100:101] offset:16
	global_load_dwordx4 v[226:229], v234, s[100:101]
	global_load_dwordx4 v[36:39], v234, s[100:101] offset:528
	global_load_dwordx4 v[32:35], v234, s[100:101] offset:512
	global_load_dwordx4 v[108:111], v235, s[100:101] offset:16
	global_load_dwordx4 v[104:107], v235, s[100:101]
	global_load_dwordx4 v[56:59], v235, s[100:101] offset:528
	global_load_dwordx4 v[52:55], v235, s[100:101] offset:512
	global_load_dwordx4 v[116:119], v236, s[100:101] offset:16
	global_load_dwordx4 v[112:115], v236, s[100:101]
	global_load_dwordx4 v[80:83], v236, s[100:101] offset:528
	global_load_dwordx4 v[72:75], v236, s[100:101] offset:512
	global_load_dwordx4 v[124:127], v237, s[100:101] offset:16
	global_load_dwordx4 v[120:123], v237, s[100:101]
	global_load_dwordx4 v[92:95], v237, s[100:101] offset:528
	global_load_dwordx4 v[88:91], v237, s[100:101] offset:512
	global_load_dwordx4 v[84:87], v238, s[100:101]
	global_load_dwordx4 v[76:79], v238, s[100:101] offset:16
	global_load_dwordx4 v[24:27], v238, s[100:101] offset:528
	global_load_dwordx4 v[28:31], v238, s[100:101] offset:512
	global_load_dwordx4 v[68:71], v239, s[100:101]
	global_load_dwordx4 v[64:67], v239, s[100:101] offset:16
	global_load_dwordx4 v[16:19], v239, s[100:101] offset:528
	global_load_dwordx4 v[20:23], v239, s[100:101] offset:512
	global_load_dwordx4 v[60:63], v240, s[100:101]
	global_load_dwordx4 v[48:51], v240, s[100:101] offset:16
	global_load_dwordx4 v[8:11], v240, s[100:101] offset:528
	global_load_dwordx4 v[12:15], v240, s[100:101] offset:512
	global_load_dwordx4 v[44:47], v241, s[100:101]
	global_load_dwordx4 v[40:43], v241, s[100:101] offset:16
	global_load_dwordx4 v[218:221], v241, s[100:101] offset:528
	global_load_dwordx4 v[222:225], v241, s[100:101] offset:512
.Lxpre_skipB:
	s_waitcnt lgkmcnt(0)
	s_barrier

; __device__ __forceinline__ int hw_lane_id() { int l; asm volatile("v_mbcnt_lo_u32_b32 %0, -1, 0\n\tv_mbcnt_hi_u32_b32 %0, -1, %0" : "=v"(l)); return l; }
; __global__ void __launch_bounds__(NWAVES * 64, 2) mega_fwd(Args args) {
;     ...
;     for (int st = 2 * ph_lo; st < 2 * ph_hi; ++st) {
;         const int ph = st >> 1, rep = st & 1;
;         bool run = true;
;         if (rep == 1) { const int ty = (ph == 0) ? 1 : (ph == NPH - 1) ? 2 : (int)((0x0804084020100804ull >> (8 * ((ph - 1) & 7))) & 255ull);
;             run = (DUPMASK & ty) != 0; }
;         if (run) {
;         const __attribute__((address_space(4))) unsigned char* kp = (const __attribute__((address_space(4))) unsigned char*)__builtin_amdgcn_kernarg_segment_ptr();
;         asm volatile("" : "+s"(kp));
;         const __attribute__((address_space(4))) Args* ap = (const __attribute__((address_space(4))) Args*)kp;
;         F.in = ap->in; F.out = ap->out; F.ws = ap->ws;
;         { int t_ = wave_s * 64 + hw_lane_id(); asm volatile("" : "+v"(t_)); F.tid = t_; F.lane = t_ & 63; F.wave = wave_s; }
.LBB0_12:
	s_ashr_i32 s57, s33, 1
	s_bitcmp1_b32 s33, 0
	s_cselect_b64 s[22:23], -1, 0
	s_and_b64 vcc, exec, s[22:23]
	s_cbranch_vccnz .LBB0_585
	s_mov_b64 s[0:1], s[66:67]
	s_waitcnt lgkmcnt(0)
	s_load_dwordx4 s[72:75], s[0:1], 0xe8
	v_mbcnt_lo_u32_b32 v0, -1, 0
	v_mbcnt_hi_u32_b32 v0, -1, v0
	s_cmp_gt_u32 s33, 1
	v_add_u32_e32 v170, s70, v0
	s_mov_b64 s[2:3], -1
	v_and_b32_e32 v172, 63, v170
	s_cbranch_scc0 .LBB0_543
	s_cmp_lg_u32 s57, 17
	s_cbranch_scc0 .LBB0_531
	s_add_i32 s85, s57, -1
	v_writelane_b32 v254, s57, 55
	s_and_b32 s6, s85, 7
	s_cmp_lt_i32 s6, 6
	v_writelane_b32 v254, s6, 56
	s_cbranch_scc1 .LBB0_17
	s_cmp_lg_u32 s6, 6
	s_mov_b64 s[8:9], 0
	s_cselect_b64 s[6:7], -1, 0
	s_branch .LBB0_18

; #define PG8_STAGE(bufoff, gbase, voff) do { _Pragma("unroll") for (int _i = 0; _i < 2; ++_i) \
;         __builtin_amdgcn_global_load_lds((const unsigned*)((const char*)(gbase) + (voff)[_i]), (PG8_LAS unsigned*)(lds + (bufoff) + ldsw + _i * 8192), 16, 0, 0); } while (0)
; #define PG8_WAIT_V(n) asm volatile("s_waitcnt vmcnt(" #n ")" ::: "memory")
; #define PG8_BAR __builtin_amdgcn_s_barrier()
; template <class Epi, class Sched, bool ALIGN_EPI = false, bool SP2 = false>
; __device__ __forceinline__ void gemm_phase(PG8_LAS unsigned char* lds, const Gemm g, const Sched& S, const Epi& E, const int wave_s) {
;     ...
;     const int tid = tid_l, wid = __builtin_amdgcn_readfirstlane(tid >> 6), lane = tid & 63, wr = wid >> 2, wc = wid & 3, fr = lane & 15, fq = lane >> 4;
;     const int K = g.K, nt = K / BK;
;     unsigned voffA[2], voffB[2];
; #pragma unroll
;     for (int i = 0; i < 2; ++i) { int R, C; stage_rc(tid * 16 + i * 8192, R, C); const int Rb = Epi::PERM ? ((R & ~31) + perm32(R & 31)) : R;
;         voffA[i] = (unsigned)(R * K + C) * 2u; voffB[i] = (unsigned)(Rb * K + C) * 2u; }
;     const size_t kstep = (size_t)(BK * 2);
;     const size_t hstep = (size_t)HALF * K * 2;
;     const size_t tstep = 2 * hstep;
;     const unsigned ldsw = (unsigned)wid * 1024u;
;     const int aoff = lds_byte(wr * 64 + fr, fq * 8), boff = lds_byte(wc * 32 + fr, fq * 8);
;     ...
;         PG8_STAGE(PG8_SB(0, 0), cB, voffB); PG8_STAGE(PG8_SA(0, 0), cA, voffA); PG8_STAGE(PG8_SB(0, 1), cB + hstep, voffB); PG8_STAGE(PG8_SA(0, 1), cA + hstep, voffA);
;         if (wr == 1) PG8_BAR;
;         PG8_WAIT_V(4); PG8_BAR;
.LBB0_356:
	v_readlane_b32 s14, v254, 56
	s_cmp_eq_u32 s14, 7
	s_cselect_b64 s[20:21], -1, 0
	s_waitcnt lgkmcnt(0)
	s_add_u32 s10, s74, 0x2b00000
	s_addc_u32 s11, s75, 0
	s_add_u32 s12, s74, 0x7000000
	s_addc_u32 s13, s75, 0
	s_cmp_eq_u32 s14, 5
	s_cselect_b64 s[18:19], -1, 0
	s_and_b64 s[8:9], s[18:19], exec
	s_cselect_b32 s3, 2, 3
	s_cmp_eq_u32 s14, 1
	v_readlane_b32 s8, v254, 59
	s_cselect_b64 s[22:23], -1, 0
	v_readlane_b32 s9, v254, 60
	s_mul_i32 s14, s8, 3
	s_and_b64 s[8:9], s[22:23], exec
	s_cselect_b32 s3, 1, s3
	s_add_i32 s3, s14, s3
	s_mul_hi_i32 s8, s3, 0x11400
	s_mul_i32 s3, s3, 0x11400
	s_add_u32 s14, s74, s3
	v_readlane_b32 s3, v254, 54
	v_cndmask_b32_e64 v174, 0.5, 1.0, s[18:19]
	s_addc_u32 s15, s75, s8
	s_and_b64 vcc, exec, s[6:7]
	s_mov_b32 s16, s3
	v_readlane_b32 s56, v254, 53
	v_readlane_b32 s85, v254, 6
	s_cbranch_vccnz .LBB0_398
	v_bfe_i32 v2, v171, 27, 1
	v_lshlrev_b32_e32 v0, 4, v171
	v_lshrrev_b32_e32 v2, 22, v2
	s_and_b64 s[6:7], s[18:19], exec
	s_mov_b32 s3, 0xc640000
	v_add_u32_e32 v2, v0, v2
	s_cselect_b32 s3, s3, 0x9280000
	v_and_b32_e32 v2, 0xfffffc00, v2
	s_add_u32 s36, s74, s3
	v_sub_u32_e32 v2, v0, v2
	s_addc_u32 s37, s75, 0
	v_ashrrev_i32_e32 v1, 31, v171
	v_lshrrev_b32_e32 v3, 4, v2
	s_and_b64 s[6:7], s[20:21], exec
	s_mov_b32 s3, 0x2580000
	v_lshrrev_b32_e32 v1, 26, v1
	v_bitop3_b32 v2, v3, v2, 32 bitop3:0x6c
	s_cselect_b32 s3, s3, 0x1880000
	s_and_b64 s[6:7], s[22:23], exec
	v_add_u32_e32 v1, v171, v1
	v_ashrrev_i32_e32 v4, 31, v2
	s_cselect_b32 s3, 0xf00000, s3
	v_ashrrev_i32_e32 v1, 6, v1
	v_lshrrev_b32_e32 v4, 26, v4
	s_add_u32 s38, s74, s3
	v_lshlrev_b32_e32 v3, 3, v1
	v_add_u32_e32 v4, v2, v4
	s_addc_u32 s39, s75, 0
	v_and_b32_e32 v3, -16, v3
	v_ashrrev_i32_e32 v5, 6, v4
	v_lshlrev_b32_e32 v1, 5, v1
	s_and_b64 s[6:7], s[18:19], exec
	v_add_u32_e32 v3, v5, v3
	v_and_b32_e32 v128, 32, v1
	v_and_b32_e32 v1, 0xc0, v4
	v_sub_u32_e32 v1, v2, v1
	v_lshlrev_b32_e32 v2, 1, v3
	v_lshrrev_b32_e32 v4, 2, v3
	v_and_b32_e32 v5, 3, v5
	s_mov_b32 s7, 0xffffe0
	s_movk_i32 s3, 0xb00
	v_ashrrev_i16_sdwa v1, v203, sext(v1) dst_sel:DWORD dst_unused:UNUSED_PAD src0_sel:DWORD src1_sel:BYTE_0
	v_and_b32_e32 v2, 24, v2
	v_and_b32_e32 v4, 4, v4
	v_and_or_b32 v5, v3, s7, v5
	s_cselect_b32 s3, 0x400, s3
	v_bfe_i32 v175, v1, 0, 16
	v_or3_b32 v2, v5, v4, v2
	v_add_u32_e32 v1, v128, v175
	v_mul_lo_u32 v212, v3, s3
	v_mul_u32_u24_e32 v2, s3, v2
	v_add_u32_e32 v0, 0x2000, v0
	v_add_lshl_u32 v176, v1, v212, 1
	v_add_lshl_u32 v178, v2, v1, 1
	v_ashrrev_i32_e32 v1, 31, v0
	v_lshrrev_b32_e32 v1, 22, v1
	v_add_u32_e32 v1, v0, v1
	v_ashrrev_i32_e32 v1, 10, v1
	v_mul_i32_i24_e32 v2, 0x400, v1
	v_sub_u32_e32 v0, v0, v2
	v_lshrrev_b32_e32 v2, 4, v0
	v_bitop3_b32 v0, v2, v0, 32 bitop3:0x6c
	v_ashrrev_i32_e32 v3, 31, v0
	v_lshrrev_b32_e32 v3, 26, v3
	v_lshlrev_b32_e32 v2, 3, v1
	v_add_u32_e32 v3, v0, v3
	v_and_b32_e32 v2, -16, v2
	v_ashrrev_i32_e32 v4, 6, v3
	v_lshlrev_b32_e32 v1, 5, v1
	v_add_u32_e32 v2, v4, v2
	v_and_b32_e32 v213, 32, v1
	v_and_b32_e32 v1, 0xc0, v3
	v_sub_u32_e32 v0, v0, v1
	v_lshlrev_b32_e32 v1, 1, v2
	v_lshrrev_b32_e32 v3, 2, v2
	v_and_b32_e32 v4, 3, v4
	v_ashrrev_i16_sdwa v0, v203, sext(v0) dst_sel:DWORD dst_unused:UNUSED_PAD src0_sel:DWORD src1_sel:BYTE_0
	v_and_b32_e32 v1, 24, v1
	v_and_b32_e32 v3, 4, v3
	v_and_or_b32 v4, v2, s7, v4
	s_ashr_i32 s7, s2, 6
	s_ashr_i32 s6, s2, 8
	v_bfe_i32 v214, v0, 0, 16
	v_or3_b32 v1, v4, v3, v1
	s_lshl_b32 s41, s7, 10
	s_lshl_b32 s7, s7, 5
	v_add_u32_e32 v0, v213, v214
	v_mul_u32_u24_e32 v1, s3, v1
	v_bfe_u32 v211, v171, 4, 2
	s_lshl_b32 s42, s6, 6
	s_and_b32 s43, s7, 0x60
	s_lshl_b32 s7, s54, 8
	v_mul_lo_u32 v215, v2, s3
	v_add_lshl_u32 v182, v1, v0, 1
	v_and_b32_e32 v210, 15, v171
	v_lshlrev_b32_e32 v1, 3, v211
	s_add_i32 s7, s7, s42
	v_add_lshl_u32 v180, v0, v215, 1
	v_or_b32_e32 v0, s7, v210
	v_lshl_or_b32 v1, s53, 8, v1
	v_or_b32_e32 v2, s43, v1
	v_ashrrev_i32_e32 v1, 31, v0
	v_ashrrev_i32_e32 v3, 31, v2
	v_lshlrev_b64 v[4:5], 12, v[0:1]
	v_lshl_add_u64 v[4:5], s[10:11], 0, v[4:5]
	v_lshlrev_b64 v[2:3], 2, v[2:3]
	v_lshl_add_u64 v[96:97], v[4:5], 0, v[2:3]
	v_or_b32_e32 v4, 16, v0
	v_ashrrev_i32_e32 v5, 31, v4
	v_lshlrev_b64 v[4:5], 12, v[4:5]
	v_lshl_add_u64 v[4:5], s[10:11], 0, v[4:5]
	v_lshl_add_u64 v[4:5], v[4:5], 0, v[2:3]
	v_or_b32_e32 v4, 32, v0
	v_ashrrev_i32_e32 v5, 31, v4
	v_or_b32_e32 v0, 48, v0
	v_lshlrev_b64 v[4:5], 12, v[4:5]
	v_ashrrev_i32_e32 v1, 31, v0
	v_lshl_add_u64 v[4:5], s[10:11], 0, v[4:5]
	v_lshlrev_b64 v[0:1], 12, v[0:1]
	v_lshl_add_u64 v[4:5], v[4:5], 0, v[2:3]
	v_lshl_add_u64 v[0:1], s[10:11], 0, v[0:1]
	v_lshl_add_u64 v[4:5], v[0:1], 0, v[2:3]
	s_mov_b32 s7, 0x80000
	v_add_co_u32_e32 v4, vcc, s7, v96
	s_mov_b32 s7, 0x90000
	s_nop 0
	v_addc_co_u32_e32 v5, vcc, 0, v97, vcc
	s_mov_b64 s[8:9], 0x80000
	s_mov_b64 s[8:9], 0x90000
	s_mov_b32 s7, 0xa0000
	s_mov_b64 s[8:9], 0xa0000
	v_add_co_u32_e32 v100, vcc, s7, v96
	s_lshl_b32 s40, s3, 9
	v_lshl_add_u64 v[98:99], v[96:97], 0, s[8:9]
	v_addc_co_u32_e32 v101, vcc, 0, v97, vcc
	s_mov_b64 s[8:9], 0xb0000
	s_lshl_b32 s88, s3, 8
	s_nop 0
	s_nop 0
	s_nop 0
	s_nop 0
	s_nop 0
	s_nop 0
	v_lshl_add_u64 v[98:99], v[96:97], 0, s[8:9]
	s_mul_i32 s8, s40, s53
	s_mov_b32 s7, 0xb0000
	s_mul_hi_i32 s9, s40, s53
	s_add_u32 s8, s38, s8
	v_add_co_u32_e32 v96, vcc, s7, v96
	s_addc_u32 s9, s39, s9
	s_add_i32 s44, s41, 0
	v_addc_co_u32_e32 v97, vcc, 0, v97, vcc
	s_add_i32 m0, s44, 0x10000
	s_mul_i32 s24, s40, s54
	global_load_lds_dwordx4 v178, s[8:9]
	s_add_i32 m0, s44, 0x12000
	s_add_u32 s16, s8, s88
	global_load_lds_dwordx4 v182, s[8:9]
	s_addc_u32 s17, s9, 0
	s_add_i32 m0, s44, 0x14000
	s_mul_hi_i32 s7, s40, s54
	global_load_lds_dwordx4 v178, s[16:17]
	s_add_i32 m0, s44, 0x16000
	s_add_u32 s34, s36, s24
	v_mov_b32_e32 v179, v129
	v_mov_b32_e32 v183, v129
	s_addc_u32 s35, s37, s7
	s_add_i32 s45, s44, 0x2000
	v_lshl_add_u64 v[188:189], s[16:17], 0, v[178:179]
	v_lshl_add_u64 v[190:191], s[16:17], 0, v[182:183]
	global_load_lds_dwordx4 v182, s[16:17]
	s_mov_b32 m0, s44
	s_add_u32 s16, s34, s88
	global_load_lds_dwordx4 v176, s[34:35]
	s_mov_b32 m0, s45
	s_addc_u32 s17, s35, 0
	s_add_i32 s46, s44, 0x4000
	global_load_lds_dwordx4 v180, s[34:35]
	s_mov_b32 m0, s46
	s_add_i32 s47, s44, 0x6000
	global_load_lds_dwordx4 v176, s[16:17]
	s_mov_b32 m0, s47
	v_mov_b32_e32 v177, v129
	global_load_lds_dwordx4 v180, s[16:17]
	v_mov_b32_e32 v181, v129
	s_cmp_eq_u32 s6, 1
	v_lshl_add_u64 v[184:185], s[8:9], 0, v[178:179]
	v_lshl_add_u64 v[186:187], s[8:9], 0, v[182:183]
	v_lshl_add_u64 v[192:193], s[34:35], 0, v[176:177]
	v_lshl_add_u64 v[194:195], s[34:35], 0, v[180:181]
	s_cselect_b64 s[24:25], -1, 0
	s_cmp_lg_u32 s6, 1
	s_cbranch_scc1 .LBB0_359
	s_barrier
; #define PG8_STAGE(bufoff, gbase, voff) do { _Pragma("unroll") for (int _i = 0; _i < 2; ++_i) \
;         __builtin_amdgcn_global_load_lds((const unsigned*)((const char*)(gbase) + (voff)[_i]), (PG8_LAS unsigned*)(lds + (bufoff) + ldsw + _i * 8192), 16, 0, 0); } while (0)
; #define PG8_WAIT_V(n) asm volatile("s_waitcnt vmcnt(" #n ")" ::: "memory")
; #define PG8_BAR __builtin_amdgcn_s_barrier()
; template <class Epi, class Sched, bool ALIGN_EPI = false, bool SP2 = false>
; __device__ __forceinline__ void gemm_phase(PG8_LAS unsigned char* lds, const Gemm g, const Sched& S, const Epi& E, const int wave_s) {
;     ...
;         PG8_WAIT_V(4); PG8_BAR;
;         PG8_STAGE(PG8_SB(1, 0), cB + kstep, voffB); PG8_STAGE(PG8_SA(1, 0), cA + kstep, voffA); PG8_STAGE(PG8_SB(1, 1), cB + hstep + kstep, voffB);
;         PG8_WAIT_V(6); PG8_BAR;
;     __device__ __forceinline__ void init(f32x4 (&acc)[2][2][4][2], const pg8::Unit& u, int wr, int wc, int fr, int fq) const {
;         const int row0 = u.pm * 256 + wr * 64 + fr, col0 = u.pn * 256 + wc * 32 + 8 * fq; const float inv = 1.0f / scale;
; #pragma unroll
;         for (int ai = 0; ai < 2; ++ai)
; #pragma unroll
;             for (int m = 0; m < 4; ++m)
; #pragma unroll
;                 for (int bj = 0; bj < 2; ++bj) { const float* xp = X + (size_t)(row0 + ai * 128 + m * 16) * D + col0 + bj * 128; acc[ai][bj][m][0] = *(const f32x4*)xp * inv; acc[ai][bj][m][1] = *(const f32x4*)(xp + 4) * inv; }
.LBB0_359:
	v_div_scale_f32 v96, s[16:17], v174, v174, 1.0
	v_rcp_f32_e32 v97, v96
	s_movk_i32 s7, 0x3c0
	s_lshl_b32 s6, s6, 13
	s_add_i32 m0, s44, 0x18000
	v_fma_f32 v98, -v96, v97, 1.0
	v_fmac_f32_e32 v97, v98, v97
	v_div_scale_f32 v98, vcc, 1.0, v174, 1.0
	v_mul_f32_e32 v99, v98, v97
	v_fma_f32 v100, -v96, v99, v98
	v_fmac_f32_e32 v99, v100, v97
	v_fma_f32 v96, -v96, v99, v98
	v_div_fmas_f32 v96, v96, v97, v99
	v_div_fixup_f32 v216, v96, v174, 1.0
	s_waitcnt vmcnt(0)
	v_pk_mul_f32 v[0:1], v[216:217], v[218:219] op_sel_hi:[0,1]
	v_pk_mul_f32 v[2:3], v[216:217], v[220:221] op_sel_hi:[0,1]
	v_pk_mul_f32 v[4:5], v[216:217], v[222:223] op_sel_hi:[0,1]
	v_pk_mul_f32 v[6:7], v[216:217], v[224:225] op_sel_hi:[0,1]
	v_pk_mul_f32 v[8:9], v[216:217], v[8:9] op_sel_hi:[0,1]
	v_pk_mul_f32 v[10:11], v[216:217], v[10:11] op_sel_hi:[0,1]
	v_pk_mul_f32 v[12:13], v[216:217], v[12:13] op_sel_hi:[0,1]
	v_pk_mul_f32 v[14:15], v[216:217], v[14:15] op_sel_hi:[0,1]
	v_pk_mul_f32 v[16:17], v[216:217], v[16:17] op_sel_hi:[0,1]
	v_pk_mul_f32 v[18:19], v[216:217], v[18:19] op_sel_hi:[0,1]
	v_pk_mul_f32 v[20:21], v[216:217], v[20:21] op_sel_hi:[0,1]
	v_pk_mul_f32 v[22:23], v[216:217], v[22:23] op_sel_hi:[0,1]
	v_pk_mul_f32 v[24:25], v[216:217], v[24:25] op_sel_hi:[0,1]
	v_pk_mul_f32 v[26:27], v[216:217], v[26:27] op_sel_hi:[0,1]
	v_pk_mul_f32 v[28:29], v[216:217], v[28:29] op_sel_hi:[0,1]
	v_pk_mul_f32 v[30:31], v[216:217], v[30:31] op_sel_hi:[0,1]
	v_pk_mul_f32 v[32:33], v[216:217], v[32:33] op_sel_hi:[0,1]
	v_pk_mul_f32 v[34:35], v[216:217], v[34:35] op_sel_hi:[0,1]
	v_pk_mul_f32 v[36:37], v[216:217], v[36:37] op_sel_hi:[0,1]
	v_pk_mul_f32 v[38:39], v[216:217], v[38:39] op_sel_hi:[0,1]
	v_pk_mul_f32 v[40:41], v[216:217], v[40:41] op_sel_hi:[0,1]
	v_pk_mul_f32 v[42:43], v[216:217], v[42:43] op_sel_hi:[0,1]
	v_pk_mul_f32 v[44:45], v[216:217], v[44:45] op_sel_hi:[0,1]
	v_pk_mul_f32 v[46:47], v[216:217], v[46:47] op_sel_hi:[0,1]
	v_pk_mul_f32 v[48:49], v[216:217], v[48:49] op_sel_hi:[0,1]
	v_pk_mul_f32 v[50:51], v[216:217], v[50:51] op_sel_hi:[0,1]
	v_pk_mul_f32 v[52:53], v[216:217], v[52:53] op_sel_hi:[0,1]
	v_pk_mul_f32 v[54:55], v[216:217], v[54:55] op_sel_hi:[0,1]
	v_pk_mul_f32 v[56:57], v[216:217], v[56:57] op_sel_hi:[0,1]
	v_pk_mul_f32 v[58:59], v[216:217], v[58:59] op_sel_hi:[0,1]
	v_pk_mul_f32 v[60:61], v[216:217], v[60:61] op_sel_hi:[0,1]
	v_pk_mul_f32 v[62:63], v[216:217], v[62:63] op_sel_hi:[0,1]
	v_pk_mul_f32 v[64:65], v[216:217], v[64:65] op_sel_hi:[0,1]
	v_pk_mul_f32 v[66:67], v[216:217], v[66:67] op_sel_hi:[0,1]
	v_pk_mul_f32 v[68:69], v[216:217], v[68:69] op_sel_hi:[0,1]
	v_pk_mul_f32 v[70:71], v[216:217], v[70:71] op_sel_hi:[0,1]
	v_pk_mul_f32 v[72:73], v[216:217], v[72:73] op_sel_hi:[0,1]
	v_pk_mul_f32 v[74:75], v[216:217], v[74:75] op_sel_hi:[0,1]
	v_pk_mul_f32 v[76:77], v[216:217], v[76:77] op_sel_hi:[0,1]
	v_pk_mul_f32 v[78:79], v[216:217], v[78:79] op_sel_hi:[0,1]
	v_pk_mul_f32 v[80:81], v[216:217], v[80:81] op_sel_hi:[0,1]
	v_pk_mul_f32 v[82:83], v[216:217], v[82:83] op_sel_hi:[0,1]
	v_pk_mul_f32 v[84:85], v[216:217], v[84:85] op_sel_hi:[0,1]
	v_pk_mul_f32 v[86:87], v[216:217], v[86:87] op_sel_hi:[0,1]
	v_pk_mul_f32 v[88:89], v[216:217], v[88:89] op_sel_hi:[0,1]
	v_pk_mul_f32 v[90:91], v[216:217], v[90:91] op_sel_hi:[0,1]
	v_pk_mul_f32 v[92:93], v[216:217], v[92:93] op_sel_hi:[0,1]
	v_pk_mul_f32 v[94:95], v[216:217], v[94:95] op_sel_hi:[0,1]
	v_pk_mul_f32 v[96:97], v[216:217], v[226:227] op_sel_hi:[0,1]
	v_pk_mul_f32 v[98:99], v[216:217], v[228:229] op_sel_hi:[0,1]
	v_pk_mul_f32 v[100:101], v[216:217], v[230:231] op_sel_hi:[0,1]
	v_pk_mul_f32 v[102:103], v[216:217], v[232:233] op_sel_hi:[0,1]
	v_pk_mul_f32 v[104:105], v[216:217], v[104:105] op_sel_hi:[0,1]
	v_pk_mul_f32 v[106:107], v[216:217], v[106:107] op_sel_hi:[0,1]
	v_pk_mul_f32 v[108:109], v[216:217], v[108:109] op_sel_hi:[0,1]
	v_pk_mul_f32 v[110:111], v[216:217], v[110:111] op_sel_hi:[0,1]
	v_pk_mul_f32 v[112:113], v[216:217], v[112:113] op_sel_hi:[0,1]
	v_pk_mul_f32 v[114:115], v[216:217], v[114:115] op_sel_hi:[0,1]
	v_pk_mul_f32 v[116:117], v[216:217], v[116:117] op_sel_hi:[0,1]
	v_pk_mul_f32 v[118:119], v[216:217], v[118:119] op_sel_hi:[0,1]
	v_pk_mul_f32 v[120:121], v[216:217], v[120:121] op_sel_hi:[0,1]
	v_pk_mul_f32 v[122:123], v[216:217], v[122:123] op_sel_hi:[0,1]
	v_pk_mul_f32 v[124:125], v[216:217], v[124:125] op_sel_hi:[0,1]
	v_pk_mul_f32 v[126:127], v[216:217], v[126:127] op_sel_hi:[0,1]
	v_or_b32_e32 v130, s42, v210
	v_lshlrev_b32_e32 v131, 6, v130
	v_lshlrev_b32_e32 v132, 4, v211
	v_lshlrev_b32_e32 v130, 2, v130
	v_and_or_b32 v131, v131, s7, v132
	v_and_b32_e32 v130, 32, v130
	v_bitop3_b32 v130, v131, s6, v130 bitop3:0xde
	v_lshl_or_b32 v131, v210, 6, v132
	v_lshlrev_b32_e32 v132, 2, v210
	s_lshl_b32 s6, s43, 7
	v_and_b32_e32 v132, 32, v132
	v_bitop3_b32 v142, v131, s6, v132 bitop3:0xde
	v_lshl_add_u64 v[132:133], v[184:185], 0, s[4:5]
	s_waitcnt vmcnt(2)
	s_barrier
	global_load_lds_dwordx4 v[132:133], off
	v_lshl_add_u64 v[132:133], v[186:187], 0, s[4:5]
	s_add_i32 m0, s44, 0x1a000
	s_add_i32 s48, s44, 0x8000
	global_load_lds_dwordx4 v[132:133], off
	v_lshl_add_u64 v[132:133], v[192:193], 0, s[4:5]
	s_mov_b32 m0, s48
	s_add_i32 s49, s44, 0xa000
	global_load_lds_dwordx4 v[132:133], off
	v_lshl_add_u64 v[132:133], v[194:195], 0, s[4:5]
	s_mov_b32 m0, s49
	s_lshr_b32 s55, s3, 6
	global_load_lds_dwordx4 v[132:133], off
	s_add_i32 m0, s44, 0x1c000
	v_lshl_add_u64 v[132:133], v[188:189], 0, s[4:5]
	global_load_lds_dwordx4 v[132:133], off
	v_lshl_add_u64 v[132:133], v[190:191], 0, s[4:5]
	s_add_i32 m0, s44, 0x1e000
	s_cmpk_lt_u32 s2, 0x100
	global_load_lds_dwordx4 v[132:133], off
	s_cselect_b64 s[26:27], -1, 0
	s_lshr_b32 s2, s3, 8
	s_and_b32 s2, s2, 14
	s_lshl_b32 s3, s2, 2
	s_sub_i32 s3, s55, s3
	s_ashr_i32 s3, s3, 1
	v_readlane_b32 s6, v253, 41
	s_cmp_lt_i32 s6, s3
	s_cselect_b32 s51, 2, 0
	s_min_i32 s3, s6, s3
	s_add_i32 s51, s51, s2
	s_mul_i32 s2, s2, s6
	s_lshl_b32 s52, s3, 1
	s_add_i32 s52, s52, s2
	v_readlane_b32 s2, v253, 42
	v_readlane_b32 s28, v254, 31
	v_readlane_b32 s3, v253, 43
	s_add_u32 s28, s72, s2
	v_readlane_b32 s29, v254, 32
	s_addc_u32 s2, s73, s3
	v_readlane_b32 s30, v254, 33
	v_readlane_b32 s31, v254, 34
	s_and_b32 s29, s2, 0xffff
	v_writelane_b32 v254, s28, 31
	v_add_u32_e32 v128, v212, v128
	v_add_lshl_u32 v128, v128, v175, 1
	v_writelane_b32 v254, s29, 32
	v_writelane_b32 v254, s30, 33
	s_waitcnt vmcnt(6)
	v_writelane_b32 v254, s31, 34
	v_lshl_add_u64 v[134:135], s[88:89], 0, v[128:129]
	v_add_u32_e32 v128, v215, v213
	v_add_lshl_u32 v128, v128, v214, 1
	v_readlane_b32 s6, v254, 54
	s_mov_b32 s50, 0
	v_mov_b32_e32 v132, v174
	v_mov_b32_e32 v133, v174
	v_lshl_add_u64 v[136:137], s[88:89], 0, v[128:129]
	s_mov_b64 s[2:3], 0
	v_add_u32_e32 v143, 0, v130
	v_readlane_b32 s56, v254, 53
	s_mov_b32 s16, s6
	s_barrier
	s_cmp_lg_u32 s50, 0
	s_cbranch_scc1 .LBB0_361
	s_branch .LBB0_362

; __device__ __forceinline__ void xcd_barrier(const XcdBarrier& b, const bool is_t0) {
;     asm volatile("s_waitcnt vmcnt(0)" ::: "memory");
;     __syncthreads();
;     if (is_t0) {
;         unsigned* bar = b.bar;
;         __builtin_amdgcn_s_waitcnt(0);
;         unsigned nloc = b.st[0], nx = b.st[1];
;         if (nloc == 0u) { xcd_barrier_complete(bar, b.x, nloc, nx); b.st[0] = nloc; b.st[1] = nx; }
;     __device__ __forceinline__ void init(f32x4 (&acc)[2][2][4][2], const pg8::Unit& u, int wr, int wc, int fr, int fq) const {
;         const int row0 = u.pm * 256 + wr * 64 + fr, col0 = u.pn * 256 + wc * 32 + 8 * fq; const float inv = 1.0f / scale;
; #pragma unroll
;         for (int ai = 0; ai < 2; ++ai)
; #pragma unroll
;             for (int m = 0; m < 4; ++m)
; #pragma unroll
;                 for (int bj = 0; bj < 2; ++bj) { const float* xp = X + (size_t)(row0 + ai * 128 + m * 16) * D + col0 + bj * 128; acc[ai][bj][m][0] = *(const f32x4*)xp * inv; acc[ai][bj][m][1] = *(const f32x4*)(xp + 4) * inv; }
;     }
.LBB0_600:
	s_waitcnt vmcnt(0)
	s_waitcnt lgkmcnt(0)
	s_barrier
	s_and_b32 s100, s57, 7
	s_movk_i32 s101, 0xa2
	s_bitcmp1_b32 s101, s100
	s_cbranch_scc0 .Lxpre_skipA
	s_cmp_eq_u32 s70, 0
	s_cbranch_scc1 .Lxpre_skipA
	v_readlane_b32 s100, v254, 4
	v_readlane_b32 s101, v254, 11
	s_lshl_b32 s100, s100, 20
	s_lshl_b32 s101, s101, 10
	s_add_i32 s100, s100, s101
	s_add_i32 s100, s100, 0x2b00000
	s_add_u32 s100, s6, s100
	s_addc_u32 s101, s7, 0
	v_mbcnt_lo_u32_b32 v240, -1, 0
	v_mbcnt_hi_u32_b32 v240, -1, v240
	v_and_b32_e32 v241, 15, v240
	v_bfe_u32 v240, v240, 4, 2
	v_lshlrev_b32_e32 v241, 12, v241
	v_lshl_or_b32 v241, v240, 5, v241
	s_lshr_b32 vcc_lo, s70, 8
	s_lshl_b32 vcc_lo, vcc_lo, 18
	s_bfe_u32 vcc_hi, s70, 0x20006
	s_lshl_b32 vcc_hi, vcc_hi, 7
	s_or_b32 vcc_lo, vcc_lo, vcc_hi
	v_or_b32_e32 v234, vcc_lo, v241
	v_add_u32_e32 v235, 0x10000, v234
	v_add_u32_e32 v236, 0x20000, v234
	v_add_u32_e32 v237, 0x30000, v234
	v_add_u32_e32 v238, 0x80000, v234
	v_add_u32_e32 v239, 0x90000, v234
	v_add_u32_e32 v240, 0xa0000, v234
	v_add_u32_e32 v241, 0xb0000, v234
	global_load_dwordx4 v[230:233], v234, s[100:101] offset:16
	global_load_dwordx4 v[226:229], v234, s[100:101]
	global_load_dwordx4 v[36:39], v234, s[100:101] offset:528
	global_load_dwordx4 v[32:35], v234, s[100:101] offset:512
	global_load_dwordx4 v[108:111], v235, s[100:101] offset:16
	global_load_dwordx4 v[104:107], v235, s[100:101]
	global_load_dwordx4 v[56:59], v235, s[100:101] offset:528
	global_load_dwordx4 v[52:55], v235, s[100:101] offset:512
	global_load_dwordx4 v[116:119], v236, s[100:101] offset:16
	global_load_dwordx4 v[112:115], v236, s[100:101]
	global_load_dwordx4 v[80:83], v236, s[100:101] offset:528
	global_load_dwordx4 v[72:75], v236, s[100:101] offset:512
	global_load_dwordx4 v[124:127], v237, s[100:101] offset:16
	global_load_dwordx4 v[120:123], v237, s[100:101]
	global_load_dwordx4 v[92:95], v237, s[100:101] offset:528
	global_load_dwordx4 v[88:91], v237, s[100:101] offset:512
	global_load_dwordx4 v[84:87], v238, s[100:101]
	global_load_dwordx4 v[76:79], v238, s[100:101] offset:16
	global_load_dwordx4 v[24:27], v238, s[100:101] offset:528
	global_load_dwordx4 v[28:31], v238, s[100:101] offset:512
	global_load_dwordx4 v[68:71], v239, s[100:101]
	global_load_dwordx4 v[64:67], v239, s[100:101] offset:16
	global_load_dwordx4 v[16:19], v239, s[100:101] offset:528
	global_load_dwordx4 v[20:23], v239, s[100:101] offset:512
	global_load_dwordx4 v[60:63], v240, s[100:101]
	global_load_dwordx4 v[48:51], v240, s[100:101] offset:16
	global_load_dwordx4 v[8:11], v240, s[100:101] offset:528
	global_load_dwordx4 v[12:15], v240, s[100:101] offset:512
	global_load_dwordx4 v[44:47], v241, s[100:101]
	global_load_dwordx4 v[40:43], v241, s[100:101] offset:16
	global_load_dwordx4 v[218:221], v241, s[100:101] offset:528
	global_load_dwordx4 v[222:225], v241, s[100:101] offset:512
.Lxpre_skipA:
	s_and_saveexec_b64 s[0:1], s[2:3]
	s_cbranch_execz .LBB0_10
	s_waitcnt vmcnt(3)
	v_mov_b32_e32 v0, s55
	s_waitcnt vmcnt(0) expcnt(0) lgkmcnt(0)
	ds_read_b32 v2, v0
	v_readlane_b32 s2, v254, 39
	s_and_b32 s48, s8, 15
	s_waitcnt lgkmcnt(0)
	v_cmp_ne_u32_e32 vcc, 0, v2
	v_mov_b32_e32 v0, s2
	ds_read_b32 v0, v0
	s_cbranch_vccnz .LBB0_616
	s_load_dwordx2 s[10:11], s[76:77], 0x4
	s_add_u32 s2, s6, 0x380200
	s_addc_u32 s3, s7, 0
	s_add_u32 s8, s6, 0x380400
	s_addc_u32 s9, s7, 0
	s_waitcnt lgkmcnt(0)
	s_mul_i32 s49, s10, s93
	s_add_u32 s10, s6, 0x380500
	s_mul_i32 s49, s49, s11
	s_addc_u32 s11, s7, 0
	s_add_u32 s12, s6, 0x380600
	s_addc_u32 s13, s7, 0
	s_add_u32 s14, s6, 0x380700
	s_addc_u32 s15, s7, 0
	s_add_u32 s16, s6, 0x380800
	s_addc_u32 s17, s7, 0
	s_add_u32 s18, s6, 0x380900
	s_addc_u32 s19, s7, 0
	s_add_u32 s20, s6, 0x380a00
	s_addc_u32 s21, s7, 0
	s_add_u32 s22, s6, 0x380b00
	s_addc_u32 s23, s7, 0
	s_add_u32 s24, s6, 0x380c00
	s_addc_u32 s25, s7, 0
	s_add_u32 s26, s6, 0x380d00
	s_addc_u32 s27, s7, 0
	s_add_u32 s28, s6, 0x380e00
	s_addc_u32 s29, s7, 0
	s_add_u32 s30, s6, 0x380f00
	s_addc_u32 s31, s7, 0
	s_add_u32 s34, s6, 0x381000
	s_addc_u32 s35, s7, 0
	s_add_u32 s36, s6, 0x381100
	s_addc_u32 s37, s7, 0
	s_add_u32 s38, s6, 0x381200
	s_addc_u32 s39, s7, 0
	s_add_u32 s40, s6, 0x381300
	s_addc_u32 s41, s7, 0
	s_mov_b32 s50, 1
	s_branch .LBB0_604
